# spatial gating item: position-scale (yf) stage reads all rstd values with 8 wide LDS reads and one wait; mixing MFMAs double-buffer their LDS fragments one d-tile ahead with counted waits, one variant
# baseline (speedup 1.0000x reference)
.LBB0_71:
	s_or_b64 exec, exec, s[50:51]
	s_waitcnt lgkmcnt(0)
	s_barrier
	s_lshl_b32 s27, s35, 15
	s_add_i32 s27, s27, 0
	ds_read_b128 v[32:35], v148
	ds_read_b128 v[36:39], v148 offset:16
	ds_read_b128 v[40:43], v148 offset:128
	ds_read_b128 v[44:47], v148 offset:144
	ds_read_b128 v[48:51], v148 offset:256
	ds_read_b128 v[52:55], v148 offset:272
	ds_read_b128 v[56:59], v148 offset:384
	ds_read_b128 v[60:63], v148 offset:400
	v_add_u32_e32 v101, s27, v87
	v_add_u32_e32 v144, s27, v103
	v_add_u32_e32 v93, s27, v139
	v_add_u32_e32 v97, s27, v142
	v_lshl_add_u32 v89, s36, 2, v99
	v_lshlrev_b32_e32 v64, 16, v28
	v_lshlrev_b32_e32 v65, 16, v29
	v_lshlrev_b32_e32 v66, 16, v30
	v_lshlrev_b32_e32 v67, 16, v31
	v_lshlrev_b32_e32 v68, 16, v24
	v_lshlrev_b32_e32 v69, 16, v25
	v_lshlrev_b32_e32 v70, 16, v26
	v_lshlrev_b32_e32 v71, 16, v27
	v_lshlrev_b32_e32 v72, 16, v20
	v_lshlrev_b32_e32 v73, 16, v21
	v_lshlrev_b32_e32 v74, 16, v22
	v_lshlrev_b32_e32 v75, 16, v23
	v_lshlrev_b32_e32 v76, 16, v16
	v_lshlrev_b32_e32 v77, 16, v17
	v_lshlrev_b32_e32 v78, 16, v18
	v_lshlrev_b32_e32 v79, 16, v19
	v_and_b32_e32 v28, 0xffff0000, v28
	v_and_b32_e32 v29, 0xffff0000, v29
	v_and_b32_e32 v30, 0xffff0000, v30
	v_and_b32_e32 v31, 0xffff0000, v31
	v_and_b32_e32 v24, 0xffff0000, v24
	v_and_b32_e32 v25, 0xffff0000, v25
	v_and_b32_e32 v26, 0xffff0000, v26
	v_and_b32_e32 v27, 0xffff0000, v27
	v_and_b32_e32 v20, 0xffff0000, v20
	v_and_b32_e32 v21, 0xffff0000, v21
	v_and_b32_e32 v22, 0xffff0000, v22
	v_and_b32_e32 v23, 0xffff0000, v23
	v_and_b32_e32 v16, 0xffff0000, v16
	v_and_b32_e32 v17, 0xffff0000, v17
	v_and_b32_e32 v18, 0xffff0000, v18
	v_and_b32_e32 v19, 0xffff0000, v19
	s_waitcnt lgkmcnt(0)
	v_mul_f32_e32 v64, v32, v64
	v_mul_f32_e32 v65, v34, v65
	v_mul_f32_e32 v66, v36, v66
	v_mul_f32_e32 v67, v38, v67
	v_mul_f32_e32 v68, v40, v68
	v_mul_f32_e32 v69, v42, v69
	v_mul_f32_e32 v70, v44, v70
	v_mul_f32_e32 v71, v46, v71
	v_mul_f32_e32 v72, v48, v72
	v_mul_f32_e32 v73, v50, v73
	v_mul_f32_e32 v74, v52, v74
	v_mul_f32_e32 v75, v54, v75
	v_mul_f32_e32 v76, v56, v76
	v_mul_f32_e32 v77, v58, v77
	v_mul_f32_e32 v78, v60, v78
	v_mul_f32_e32 v79, v62, v79
	v_mul_f32_e32 v28, v33, v28
	v_mul_f32_e32 v29, v35, v29
	v_mul_f32_e32 v30, v37, v30
	v_mul_f32_e32 v31, v39, v31
	v_mul_f32_e32 v24, v41, v24
	v_mul_f32_e32 v25, v43, v25
	v_mul_f32_e32 v26, v45, v26
	v_mul_f32_e32 v27, v47, v27
	v_mul_f32_e32 v20, v49, v20
	v_mul_f32_e32 v21, v51, v21
	v_mul_f32_e32 v22, v53, v22
	v_mul_f32_e32 v23, v55, v23
	v_mul_f32_e32 v16, v57, v16
	v_mul_f32_e32 v17, v59, v17
	v_mul_f32_e32 v18, v61, v18
	v_mul_f32_e32 v19, v63, v19
	v_cvt_pk_bf16_f32 v28, v64, v28
	v_cvt_pk_bf16_f32 v29, v65, v29
	v_cvt_pk_bf16_f32 v30, v66, v30
	v_cvt_pk_bf16_f32 v31, v67, v31
	v_cvt_pk_bf16_f32 v24, v68, v24
	v_cvt_pk_bf16_f32 v25, v69, v25
	v_cvt_pk_bf16_f32 v26, v70, v26
	v_cvt_pk_bf16_f32 v27, v71, v27
	v_cvt_pk_bf16_f32 v20, v72, v20
	v_cvt_pk_bf16_f32 v21, v73, v21
	v_cvt_pk_bf16_f32 v22, v74, v22
	v_cvt_pk_bf16_f32 v23, v75, v23
	v_cvt_pk_bf16_f32 v16, v76, v16
	v_cvt_pk_bf16_f32 v17, v77, v17
	v_cvt_pk_bf16_f32 v18, v78, v18
	v_cvt_pk_bf16_f32 v19, v79, v19
	s_and_b64 vcc, exec, s[38:39]
	s_cbranch_vccnz .Lsp_n2
	ds_read_b128 v[216:219], v101
	ds_read_b128 v[220:223], v144
	ds_read_b128 v[224:227], v93
	ds_read_b128 v[228:231], v97
	ds_read_b128 v[40:43], v89
	ds_read_b128 v[232:235], v101 offset:4096
	ds_read_b128 v[236:239], v144 offset:4096
	ds_read_b128 v[240:243], v93 offset:4096
	ds_read_b128 v[244:247], v97 offset:4096
	ds_read_b128 v[52:55], v89 offset:64
	s_waitcnt lgkmcnt(6)
	v_mfma_f32_16x16x32_bf16 v[32:35], v[216:219], v[28:31], 0
	v_mfma_f32_16x16x32_bf16 v[32:35], v[220:223], v[24:27], v[32:35]
	v_mfma_f32_16x16x32_bf16 v[32:35], v[224:227], v[20:23], v[32:35]
	v_mfma_f32_16x16x32_bf16 v[32:35], v[228:231], v[16:19], v[32:35]
	ds_read_b128 v[216:219], v101 offset:8192
	ds_read_b128 v[220:223], v144 offset:8192
	ds_read_b128 v[224:227], v93 offset:8192
	ds_read_b128 v[228:231], v97 offset:8192
	ds_read_b128 v[60:63], v89 offset:128
	s_waitcnt lgkmcnt(6)
	v_mfma_f32_16x16x32_bf16 v[36:39], v[232:235], v[28:31], 0
	v_mfma_f32_16x16x32_bf16 v[36:39], v[236:239], v[24:27], v[36:39]
	v_mfma_f32_16x16x32_bf16 v[36:39], v[240:243], v[20:23], v[36:39]
	v_mfma_f32_16x16x32_bf16 v[36:39], v[244:247], v[16:19], v[36:39]
	ds_read_b128 v[232:235], v101 offset:12288
	ds_read_b128 v[236:239], v144 offset:12288
	ds_read_b128 v[240:243], v93 offset:12288
	ds_read_b128 v[244:247], v97 offset:12288
	ds_read_b128 v[68:71], v89 offset:192
	s_waitcnt lgkmcnt(6)
	v_mfma_f32_16x16x32_bf16 v[44:47], v[216:219], v[28:31], 0
	v_mfma_f32_16x16x32_bf16 v[44:47], v[220:223], v[24:27], v[44:47]
	v_mfma_f32_16x16x32_bf16 v[44:47], v[224:227], v[20:23], v[44:47]
	v_mfma_f32_16x16x32_bf16 v[44:47], v[228:231], v[16:19], v[44:47]
	ds_read_b128 v[216:219], v101 offset:16384
	ds_read_b128 v[220:223], v144 offset:16384
	ds_read_b128 v[224:227], v93 offset:16384
	ds_read_b128 v[228:231], v97 offset:16384
	ds_read_b128 v[76:79], v89 offset:256
	s_waitcnt lgkmcnt(6)
	v_mfma_f32_16x16x32_bf16 v[48:51], v[232:235], v[28:31], 0
	v_mfma_f32_16x16x32_bf16 v[48:51], v[236:239], v[24:27], v[48:51]
	v_mfma_f32_16x16x32_bf16 v[48:51], v[240:243], v[20:23], v[48:51]
	v_mfma_f32_16x16x32_bf16 v[48:51], v[244:247], v[16:19], v[48:51]
	ds_read_b128 v[232:235], v101 offset:20480
	ds_read_b128 v[236:239], v144 offset:20480
	ds_read_b128 v[240:243], v93 offset:20480
	ds_read_b128 v[244:247], v97 offset:20480
	ds_read_b128 v[80:83], v89 offset:320
	s_waitcnt lgkmcnt(6)
	v_mfma_f32_16x16x32_bf16 v[56:59], v[216:219], v[28:31], 0
	v_mfma_f32_16x16x32_bf16 v[56:59], v[220:223], v[24:27], v[56:59]
	v_mfma_f32_16x16x32_bf16 v[56:59], v[224:227], v[20:23], v[56:59]
	v_mfma_f32_16x16x32_bf16 v[56:59], v[228:231], v[16:19], v[56:59]
	ds_read_b128 v[216:219], v101 offset:24576
	ds_read_b128 v[220:223], v144 offset:24576
	ds_read_b128 v[224:227], v93 offset:24576
	ds_read_b128 v[228:231], v97 offset:24576
	s_waitcnt lgkmcnt(5)
	v_mfma_f32_16x16x32_bf16 v[64:67], v[232:235], v[28:31], 0
	v_mfma_f32_16x16x32_bf16 v[64:67], v[236:239], v[24:27], v[64:67]
	v_mfma_f32_16x16x32_bf16 v[64:67], v[240:243], v[20:23], v[64:67]
	v_mfma_f32_16x16x32_bf16 v[64:67], v[244:247], v[16:19], v[64:67]
	ds_read_b128 v[232:235], v101 offset:28672
	ds_read_b128 v[236:239], v144 offset:28672
	ds_read_b128 v[240:243], v93 offset:28672
	ds_read_b128 v[244:247], v97 offset:28672
	s_waitcnt lgkmcnt(4)
	v_mfma_f32_16x16x32_bf16 v[72:75], v[216:219], v[28:31], 0
	v_mfma_f32_16x16x32_bf16 v[72:75], v[220:223], v[24:27], v[72:75]
	v_mfma_f32_16x16x32_bf16 v[72:75], v[224:227], v[20:23], v[72:75]
	v_mfma_f32_16x16x32_bf16 v[72:75], v[228:231], v[16:19], v[72:75]
	s_waitcnt lgkmcnt(0)
	v_mfma_f32_16x16x32_bf16 v[248:251], v[232:235], v[28:31], 0
	ds_read_b128 v[28:31], v89 offset:384
	v_mfma_f32_16x16x32_bf16 v[24:27], v[236:239], v[24:27], v[248:251]
	v_mfma_f32_16x16x32_bf16 v[24:27], v[240:243], v[20:23], v[24:27]
	v_mfma_f32_16x16x32_bf16 v[24:27], v[244:247], v[16:19], v[24:27]
	s_waitcnt lgkmcnt(1)
	s_branch .LBB0_59
.Lsp_n2:
	ds_read_b128 v[216:219], v101
	ds_read_b128 v[220:223], v144
	ds_read_b128 v[40:43], v89
	ds_read_b128 v[232:235], v101 offset:4096
	ds_read_b128 v[236:239], v144 offset:4096
	ds_read_b128 v[52:55], v89 offset:64
	s_waitcnt lgkmcnt(4)
	v_mfma_f32_16x16x32_bf16 v[32:35], v[216:219], v[28:31], 0
	v_mfma_f32_16x16x32_bf16 v[32:35], v[220:223], v[24:27], v[32:35]
	ds_read_b128 v[216:219], v101 offset:8192
	ds_read_b128 v[220:223], v144 offset:8192
	ds_read_b128 v[60:63], v89 offset:128
	s_waitcnt lgkmcnt(4)
	v_mfma_f32_16x16x32_bf16 v[36:39], v[232:235], v[28:31], 0
	v_mfma_f32_16x16x32_bf16 v[36:39], v[236:239], v[24:27], v[36:39]
	ds_read_b128 v[232:235], v101 offset:12288
	ds_read_b128 v[236:239], v144 offset:12288
	ds_read_b128 v[68:71], v89 offset:192
	s_waitcnt lgkmcnt(4)
	v_mfma_f32_16x16x32_bf16 v[44:47], v[216:219], v[28:31], 0
	v_mfma_f32_16x16x32_bf16 v[44:47], v[220:223], v[24:27], v[44:47]
	ds_read_b128 v[216:219], v101 offset:16384
	ds_read_b128 v[220:223], v144 offset:16384
	ds_read_b128 v[76:79], v89 offset:256
	s_waitcnt lgkmcnt(4)
	v_mfma_f32_16x16x32_bf16 v[48:51], v[232:235], v[28:31], 0
	v_mfma_f32_16x16x32_bf16 v[48:51], v[236:239], v[24:27], v[48:51]
	ds_read_b128 v[232:235], v101 offset:20480
	ds_read_b128 v[236:239], v144 offset:20480
	ds_read_b128 v[80:83], v89 offset:320
	s_waitcnt lgkmcnt(4)
	v_mfma_f32_16x16x32_bf16 v[56:59], v[216:219], v[28:31], 0
	v_mfma_f32_16x16x32_bf16 v[56:59], v[220:223], v[24:27], v[56:59]
	ds_read_b128 v[216:219], v101 offset:24576
	ds_read_b128 v[220:223], v144 offset:24576
	s_waitcnt lgkmcnt(3)
	v_mfma_f32_16x16x32_bf16 v[64:67], v[232:235], v[28:31], 0
	v_mfma_f32_16x16x32_bf16 v[64:67], v[236:239], v[24:27], v[64:67]
	ds_read_b128 v[232:235], v101 offset:28672
	ds_read_b128 v[236:239], v144 offset:28672
	s_waitcnt lgkmcnt(2)
	v_mfma_f32_16x16x32_bf16 v[72:75], v[216:219], v[28:31], 0
	v_mfma_f32_16x16x32_bf16 v[72:75], v[220:223], v[24:27], v[72:75]
	s_waitcnt lgkmcnt(0)
	v_mfma_f32_16x16x32_bf16 v[248:251], v[232:235], v[28:31], 0
	ds_read_b128 v[28:31], v89 offset:384
	v_mfma_f32_16x16x32_bf16 v[24:27], v[236:239], v[24:27], v[248:251]
	s_waitcnt lgkmcnt(1)
	s_branch .LBB0_59
